# NSA slow-path QK^T: K fragments through a 3-deep register ring so LDS reads run ahead of the MFMA chain
# speedup vs baseline: 1.0433x; 1.0046x over previous
; DI int otid() { int z; asm volatile("s_mov_b32 %0, 0" : "=s"(z)); return (int)threadIdx.x + z; }
; __global__ void __launch_bounds__(256, LB2) mega(Params p, int ph_lo, int ph_hi) {
;     ...
;       for (;;) {
;         const int i_ = fetch_task(CTR + 64 + ph * 8 + xq_);
;         if (i_ >= 128) break;
;         const int tt_ = 2 * ((i_ >> 1) * 8 + xq_) + (i_ & 1);
;         const int t = tt_ >> 1;
;         const int tid = otid(), lane = tid & 63, w = tid >> 6, r = lane & 31, h = lane >> 5;
;         int zt_;
;         asm volatile("s_mov_b32 %0, 0" : "=s"(zt_));
;         char* const ws = ws_ph + zt_;
;         if ((tt_ & 1) == 0) {
.LBB0_462:
	v_add_u32_e32 v212, 0x500, v189
	v_mov_b32_e32 v219, 0x12410
	v_mov_b32_e32 v213, 0x12400
	v_mov_b32_e32 v214, 0x12404
	v_mov_b32_e32 v215, 0x461c4000
	v_mov_b32_e32 v216, 0x37000000
	v_mov_b32_e32 v217, 0x3c0881c4
	v_mov_b32_e32 v218, 0xbab64f3b
	v_mov_b32_e32 v224, 0x7f800000
	v_mov_b32_e32 v225, 0xffffffc0
	v_mov_b32_e32 v226, 0xffffffe0
	v_mov_b32_e32 v227, 0x7fc00000
	v_mov_b32_e32 v229, 0x3ecc95a3
	v_mov_b32_e32 v231, 0x12000
	v_mov_b32_e32 v232, 0x3fe
	v_mov_b32_e32 v188, 0x358637bd
	v_mov_b32_e32 v190, 0x3f317218
	s_and_b64 vcc, exec, s[0:1]
	s_cbranch_vccnz .LBB0_458

; #define MFMA32(a, b, c) __builtin_amdgcn_mfma_f32_32x32x16_bf16((a), (b), (c), 0, 0, 0)
;   DI float aux(int key) const { return (cuml[key] + cpre[key >> 7]) * LOG2E; }
;   DI float aux(int key) const { return __int_as_float(pos[key]); }
;   DI float score(float s, int, float, int t) const { return mine(t) ? s * sc + bfar : NEG; }
;   DI float aux(int key) const { return __int_as_float(pos[key]); }
; template <int DK, bool PV, class SF, class PH>
; DI void attn_tile(const bf16x8 (&qf)[DK / 16], f32x16 (&o)[4], float& m, float& l, const char* smem, SF sf, PH ph) {
;     ...
;   for (int kb = 0; kb < 2; ++kb) {
; #pragma unroll
;     for (int i = 0; i < 16; ++i) s[kb][i] = 0.f;
; #pragma unroll
;     for (int ks = 0; ks < DK / 16; ++ks) {
;       bf16x8 a = *(const bf16x8*)(Ks + (kb * 32 + r) * (DK + 8) + ks * 16 + h * 8);
;       s[kb] = MFMA32(a, qf[ks], s[kb]);
;     }
;   }
;           DI float aux(int key) const { int n = key < 511 ? key : 510; return __int_as_float(pos[16 * n + 31]); }
;           DI float score(float s, int key, float ax, int) const {
;             bool valid = (16 * key + 31 <= tq) && key < 511;
;             int d = posq - __float_as_int(ax);
;             d = d < 0 ? 0 : (d > 799 ? 799 : d);
;             return valid ? s * sc + lutr[d] : NEG;
;           }
.LBB0_485:
	s_or_b64 exec, exec, s[10:11]
	s_waitcnt vmcnt(7)
	ds_write_b128 v38, v[2:5]
	s_waitcnt vmcnt(6)
	ds_write_b128 v39, v[6:9]
	s_waitcnt vmcnt(5)
	ds_write_b128 v40, v[10:13]
	s_waitcnt vmcnt(4)
	ds_write_b128 v41, v[14:17]
	s_waitcnt vmcnt(3)
	ds_write2_b64 v43, v[18:19], v[20:21] offset1:1
	s_waitcnt vmcnt(2)
	ds_write2_b64 v44, v[22:23], v[24:25] offset1:1
	s_waitcnt vmcnt(1)
	ds_write2_b64 v45, v[26:27], v[28:29] offset1:1
	s_waitcnt vmcnt(0)
	ds_write2_b64 v46, v[30:31], v[32:33] offset1:1
	s_and_saveexec_b64 s[10:11], vcc
	ds_write_b32 v35, v0 offset:43008
	s_or_b64 exec, exec, s[10:11]
	s_waitcnt lgkmcnt(0)
	s_barrier
	s_mov_b32 s10, 0
	s_nop 0
	v_add_u32_e32 v0, s10, v189
	v_bfe_u32 v48, v0, 5, 1
	v_and_b32_e32 v2, 31, v0
	v_lshlrev_b32_e32 v50, 4, v48
	v_mad_u32_u24 v0, v2, s73, v50
	ds_read_b128 v[212:215], v0
	ds_read_b128 v[216:219], v0 offset:32
	ds_read_b128 v[224:227], v0 offset:64
	s_waitcnt lgkmcnt(2)
	v_mfma_f32_32x32x16_bf16 v[18:33], v[212:215], v[136:139], 0
	ds_read_b128 v[212:215], v0 offset:96
	v_lshl_add_u32 v49, v48, 6, s37
	s_waitcnt lgkmcnt(2)
	v_mfma_f32_32x32x16_bf16 v[18:33], v[216:219], v[112:115], v[18:33]
	ds_read_b128 v[216:219], v0 offset:128
	s_waitcnt lgkmcnt(2)
	v_mfma_f32_32x32x16_bf16 v[18:33], v[224:227], v[116:119], v[18:33]
	ds_read_b128 v[224:227], v0 offset:160
	s_waitcnt lgkmcnt(2)
	v_mfma_f32_32x32x16_bf16 v[18:33], v[212:215], v[120:123], v[18:33]
	ds_read_b128 v[212:215], v0 offset:192
	s_waitcnt lgkmcnt(2)
	v_mfma_f32_32x32x16_bf16 v[18:33], v[216:219], v[124:127], v[18:33]
	ds_read_b128 v[216:219], v0 offset:224
	s_waitcnt lgkmcnt(2)
	v_mfma_f32_32x32x16_bf16 v[18:33], v[224:227], v[128:131], v[18:33]
	ds_read_b128 v[224:227], v0 offset:8704
	s_waitcnt lgkmcnt(2)
	v_mfma_f32_32x32x16_bf16 v[18:33], v[212:215], v[132:135], v[18:33]
	ds_read_b128 v[212:215], v0 offset:8736
	s_waitcnt lgkmcnt(2)
	v_mfma_f32_32x32x16_bf16 v[18:33], v[216:219], v[140:143], v[18:33]
	ds_read_b128 v[216:219], v0 offset:8768
	s_waitcnt lgkmcnt(2)
	v_mfma_f32_32x32x16_bf16 v[2:17], v[224:227], v[136:139], 0
	ds_read_b128 v[224:227], v0 offset:8800
	s_waitcnt lgkmcnt(2)
	v_mfma_f32_32x32x16_bf16 v[2:17], v[212:215], v[112:115], v[2:17]
	ds_read_b128 v[212:215], v0 offset:8832
	s_waitcnt lgkmcnt(2)
	v_mfma_f32_32x32x16_bf16 v[2:17], v[216:219], v[116:119], v[2:17]
	ds_read_b128 v[216:219], v0 offset:8864
	s_waitcnt lgkmcnt(2)
	v_mfma_f32_32x32x16_bf16 v[2:17], v[224:227], v[120:123], v[2:17]
	ds_read_b128 v[224:227], v0 offset:8896
	s_waitcnt lgkmcnt(2)
	v_mfma_f32_32x32x16_bf16 v[2:17], v[212:215], v[124:127], v[2:17]
	ds_read_b128 v[212:215], v0 offset:8928
	s_waitcnt lgkmcnt(2)
	v_mfma_f32_32x32x16_bf16 v[2:17], v[216:219], v[128:131], v[2:17]
	s_waitcnt lgkmcnt(1)
	v_mfma_f32_32x32x16_bf16 v[2:17], v[224:227], v[132:135], v[2:17]
	v_lshlrev_b32_e32 v0, 2, v48
	v_lshl_add_u64 v[36:37], s[14:15], 0, v[0:1]
	v_add_u32_e32 v37, 0xfffffc50, v49
	v_cmp_le_i32_e64 s[10:11], v37, v150
	v_cmp_gt_u32_e64 s[12:13], s78, v36
	s_and_b64 s[12:13], s[12:13], s[10:11]
	s_waitcnt lgkmcnt(0)
	v_mfma_f32_32x32x16_bf16 v[2:17], v[212:215], v[140:143], v[2:17]
	v_mov_b32_e32 v37, 0xf149f2ca
	v_mov_b32_e32 v48, 0xf149f2ca
	v_and_b32_e32 v226, 32, v189
	v_lshrrev_b32_e32 v226, 1, v226
	ds_read_b32 v213, v226 offset:43008
	ds_read_b32 v214, v226 offset:43012
	ds_read_b32 v215, v226 offset:43016
	ds_read_b32 v216, v226 offset:43020
	ds_read_b32 v217, v226 offset:43040
	ds_read_b32 v218, v226 offset:43044
	ds_read_b32 v224, v226 offset:43048
	ds_read_b32 v225, v226 offset:43052
	s_waitcnt lgkmcnt(0)
	v_sub_u32_e32 v213, v162, v213
	v_med3_i32 v213, v213, 0, v236
	v_lshl_add_u32 v213, v213, 2, v163
	ds_read_b32 v213, v213 offset:43264
	v_sub_u32_e32 v214, v162, v214
	v_med3_i32 v214, v214, 0, v236
	v_lshl_add_u32 v214, v214, 2, v163
	ds_read_b32 v214, v214 offset:43264
	v_sub_u32_e32 v215, v162, v215
	v_med3_i32 v215, v215, 0, v236
	v_lshl_add_u32 v215, v215, 2, v163
	ds_read_b32 v215, v215 offset:43264
	v_sub_u32_e32 v216, v162, v216
	v_med3_i32 v216, v216, 0, v236
	v_lshl_add_u32 v216, v216, 2, v163
	ds_read_b32 v216, v216 offset:43264
	v_sub_u32_e32 v217, v162, v217
	v_med3_i32 v217, v217, 0, v236
	v_lshl_add_u32 v217, v217, 2, v163
	ds_read_b32 v217, v217 offset:43264
	v_sub_u32_e32 v218, v162, v218
	v_med3_i32 v218, v218, 0, v236
	v_lshl_add_u32 v218, v218, 2, v163
	ds_read_b32 v218, v218 offset:43264
	v_sub_u32_e32 v224, v162, v224
	v_med3_i32 v224, v224, 0, v236
	v_lshl_add_u32 v224, v224, 2, v163
	ds_read_b32 v224, v224 offset:43264
	v_sub_u32_e32 v225, v162, v225
	v_med3_i32 v225, v225, 0, v236
	v_lshl_add_u32 v225, v225, 2, v163
	ds_read_b32 v225, v225 offset:43264
	s_waitcnt lgkmcnt(0)
	v_fmac_f32_e32 v213, 0x3e0293ee, v18
	v_cndmask_b32_e64 v48, v48, v213, s[12:13]

; #define MFMA32(a, b, c) __builtin_amdgcn_mfma_f32_32x32x16_bf16((a), (b), (c), 0, 0, 0)
;   DI float score(float s, int, float, int t) const { return mine(t) ? s * sc + bfar : NEG; }
; template <int DK, bool PV, class SF, class PH>
; DI void attn_tile(const bf16x8 (&qf)[DK / 16], f32x16 (&o)[4], float& m, float& l, const char* smem, SF sf, PH ph) {
;     ...
;   for (int kb = 0; kb < 2; ++kb) {
; #pragma unroll
;     for (int i = 0; i < 16; ++i) s[kb][i] = 0.f;
; #pragma unroll
;     for (int ks = 0; ks < DK / 16; ++ks) {
;       bf16x8 a = *(const bf16x8*)(Ks + (kb * 32 + r) * (DK + 8) + ks * 16 + h * 8);
;       s[kb] = MFMA32(a, qf[ks], s[kb]);
;     }
;   }
;           DI float score(float s, int key, float ax, int) const {
;             bool valid = (16 * key + 31 <= tq) && key < 511;
;             int d = posq - __float_as_int(ax);
;             d = d < 0 ? 0 : (d > 799 ? 799 : d);
;             return valid ? s * sc + lutr[d] : NEG;
;           }
.LBB0_558:
	s_or_b64 exec, exec, s[12:13]
	s_waitcnt vmcnt(7)
	ds_write_b128 v158, v[2:5]
	s_waitcnt vmcnt(6)
	ds_write_b128 v159, v[6:9]
	s_waitcnt vmcnt(5)
	ds_write_b128 v169, v[10:13]
	s_waitcnt vmcnt(4)
	ds_write_b128 v170, v[80:83]
	s_waitcnt vmcnt(3)
	ds_write2_b64 v171, v[84:85], v[86:87] offset1:1
	s_waitcnt vmcnt(2)
	ds_write2_b64 v172, v[88:89], v[90:91] offset1:1
	s_waitcnt vmcnt(1)
	ds_write2_b64 v173, v[92:93], v[94:95] offset1:1
	s_waitcnt vmcnt(0)
	ds_write2_b64 v174, v[96:97], v[98:99] offset1:1
	s_and_saveexec_b64 s[12:13], s[10:11]
	ds_write_b32 v149, v0 offset:43008
	s_or_b64 exec, exec, s[12:13]
	s_waitcnt lgkmcnt(0)
	s_barrier
	s_mov_b32 s12, 0
	v_mov_b32_e32 v7, 0xf149f2ca
	v_add_u32_e32 v0, s12, v189
	v_bfe_u32 v5, v0, 5, 1
	v_and_b32_e32 v4, 31, v0
	v_lshlrev_b32_e32 v9, 4, v5
	v_mad_u32_u24 v0, v4, s73, v9
	ds_read_b128 v[212:215], v0
	ds_read_b128 v[216:219], v0 offset:32
	ds_read_b128 v[224:227], v0 offset:64
	s_waitcnt lgkmcnt(2)
	v_mfma_f32_32x32x16_bf16 v[96:111], v[212:215], v[136:139], 0
	ds_read_b128 v[212:215], v0 offset:96
	v_mov_b32_e32 v8, 0xf149f2ca
	s_waitcnt lgkmcnt(2)
	v_mfma_f32_32x32x16_bf16 v[96:111], v[216:219], v[112:115], v[96:111]
	ds_read_b128 v[216:219], v0 offset:128
	s_waitcnt lgkmcnt(2)
	v_mfma_f32_32x32x16_bf16 v[96:111], v[224:227], v[116:119], v[96:111]
	ds_read_b128 v[224:227], v0 offset:160
	s_waitcnt lgkmcnt(2)
	v_mfma_f32_32x32x16_bf16 v[96:111], v[212:215], v[120:123], v[96:111]
	ds_read_b128 v[212:215], v0 offset:192
	s_waitcnt lgkmcnt(2)
	v_mfma_f32_32x32x16_bf16 v[96:111], v[216:219], v[124:127], v[96:111]
	ds_read_b128 v[216:219], v0 offset:224
	s_waitcnt lgkmcnt(2)
	v_mfma_f32_32x32x16_bf16 v[96:111], v[224:227], v[128:131], v[96:111]
	ds_read_b128 v[224:227], v0 offset:8704
	s_waitcnt lgkmcnt(2)
	v_mfma_f32_32x32x16_bf16 v[96:111], v[212:215], v[132:135], v[96:111]
	ds_read_b128 v[212:215], v0 offset:8736
	s_waitcnt lgkmcnt(2)
	v_mfma_f32_32x32x16_bf16 v[96:111], v[216:219], v[140:143], v[96:111]
	ds_read_b128 v[216:219], v0 offset:8768
	s_waitcnt lgkmcnt(2)
	v_mfma_f32_32x32x16_bf16 v[80:95], v[224:227], v[136:139], 0
	ds_read_b128 v[224:227], v0 offset:8800
	s_waitcnt lgkmcnt(2)
	v_mfma_f32_32x32x16_bf16 v[80:95], v[212:215], v[112:115], v[80:95]
	ds_read_b128 v[212:215], v0 offset:8832
	s_waitcnt lgkmcnt(2)
	v_mfma_f32_32x32x16_bf16 v[80:95], v[216:219], v[116:119], v[80:95]
	ds_read_b128 v[216:219], v0 offset:8864
	s_waitcnt lgkmcnt(2)
	v_mfma_f32_32x32x16_bf16 v[80:95], v[224:227], v[120:123], v[80:95]
	ds_read_b128 v[224:227], v0 offset:8896
	s_waitcnt lgkmcnt(2)
	v_mfma_f32_32x32x16_bf16 v[80:95], v[212:215], v[124:127], v[80:95]
	ds_read_b128 v[212:215], v0 offset:8928
	s_waitcnt lgkmcnt(2)
	v_mfma_f32_32x32x16_bf16 v[80:95], v[216:219], v[128:131], v[80:95]
	s_waitcnt lgkmcnt(1)
	v_mfma_f32_32x32x16_bf16 v[80:95], v[224:227], v[132:135], v[80:95]
	v_lshlrev_b32_e32 v0, 2, v5
	v_lshl_add_u64 v[2:3], s[26:27], 0, v[0:1]
	v_lshl_add_u32 v3, v5, 6, s36
	v_add_u32_e32 v5, 0xfffffc50, v3
	v_cmp_le_i32_e32 vcc, v5, v150
	v_cmp_gt_u32_e64 s[12:13], s78, v2
	s_waitcnt lgkmcnt(0)
	v_mfma_f32_32x32x16_bf16 v[80:95], v[212:215], v[140:143], v[80:95]
	s_and_b64 s[44:45], s[12:13], vcc
	v_and_b32_e32 v226, 32, v189
	v_lshrrev_b32_e32 v226, 1, v226
	ds_read_b32 v213, v226 offset:43008
	ds_read_b32 v214, v226 offset:43012
	ds_read_b32 v215, v226 offset:43016
	ds_read_b32 v216, v226 offset:43020
	ds_read_b32 v217, v226 offset:43040
	ds_read_b32 v218, v226 offset:43044
	ds_read_b32 v224, v226 offset:43048
	ds_read_b32 v225, v226 offset:43052
	s_waitcnt lgkmcnt(0)
	v_sub_u32_e32 v213, v162, v213
	v_med3_i32 v213, v213, 0, v236
	v_lshl_add_u32 v213, v213, 2, v163
	ds_read_b32 v213, v213 offset:43264
	v_sub_u32_e32 v214, v162, v214
	v_med3_i32 v214, v214, 0, v236
	v_lshl_add_u32 v214, v214, 2, v163
	ds_read_b32 v214, v214 offset:43264
	v_sub_u32_e32 v215, v162, v215
	v_med3_i32 v215, v215, 0, v236
	v_lshl_add_u32 v215, v215, 2, v163
	ds_read_b32 v215, v215 offset:43264
	v_sub_u32_e32 v216, v162, v216
	v_med3_i32 v216, v216, 0, v236
	v_lshl_add_u32 v216, v216, 2, v163
	ds_read_b32 v216, v216 offset:43264
	v_sub_u32_e32 v217, v162, v217
	v_med3_i32 v217, v217, 0, v236
	v_lshl_add_u32 v217, v217, 2, v163
	ds_read_b32 v217, v217 offset:43264
	v_sub_u32_e32 v218, v162, v218
	v_med3_i32 v218, v218, 0, v236
	v_lshl_add_u32 v218, v218, 2, v163
	ds_read_b32 v218, v218 offset:43264
	v_sub_u32_e32 v224, v162, v224
	v_med3_i32 v224, v224, 0, v236
	v_lshl_add_u32 v224, v224, 2, v163
	ds_read_b32 v224, v224 offset:43264
	v_sub_u32_e32 v225, v162, v225
	v_med3_i32 v225, v225, 0, v236
	v_lshl_add_u32 v225, v225, 2, v163
	ds_read_b32 v225, v225 offset:43264
	s_waitcnt lgkmcnt(0)
	v_fmac_f32_e32 v213, 0x3e0293ee, v96
	v_cndmask_b32_e64 v8, v8, v213, s[44:45]

; #define MFMA32(a, b, c) __builtin_amdgcn_mfma_f32_32x32x16_bf16((a), (b), (c), 0, 0, 0)
;   DI float score(float s, int, float, int t) const { return mine(t) ? s * sc + bfar : NEG; }
; template <int DK, bool PV, class SF, class PH>
; DI void attn_tile(const bf16x8 (&qf)[DK / 16], f32x16 (&o)[4], float& m, float& l, const char* smem, SF sf, PH ph) {
;     ...
;   for (int kb = 0; kb < 2; ++kb) {
; #pragma unroll
;     for (int i = 0; i < 16; ++i) s[kb][i] = 0.f;
; #pragma unroll
;     for (int ks = 0; ks < DK / 16; ++ks) {
;       bf16x8 a = *(const bf16x8*)(Ks + (kb * 32 + r) * (DK + 8) + ks * 16 + h * 8);
;       s[kb] = MFMA32(a, qf[ks], s[kb]);
;     }
;   }
;   DI float score(float s, int key, float ax, int t) const {
;     bool valid = mine(t) && key <= tq;
;     int d = posq - __float_as_int(ax);
;     d = d < 0 ? 0 : (d > 799 ? 799 : d);
;     return valid ? s * sc + lutr[d] : NEG;
;   }
.LBB0_679:
	s_cmp_lt_u32 s46, 64
	s_cselect_b64 s[12:13], -1, 0
	s_cmp_gt_u32 s46, 63
	v_lshrrev_b64 v[2:3], s46, v[144:145]
	v_cndmask_b32_e64 v0, 0, 1, s[12:13]
	s_cselect_b64 s[12:13], -1, 0
	v_lshrrev_b64 v[4:5], s46, v[146:147]
	v_cndmask_b32_e64 v3, 0, 1, s[12:13]
	v_and_b32_e32 v0, v0, v2
	v_and_b32_e32 v3, v3, v4
	v_or_b32_e32 v0, v3, v0
	v_cmp_ne_u64_e32 vcc, 0, v[0:1]
	s_cbranch_vccz .LBB0_665
	s_mov_b32 s12, 0
	v_and_b32_e32 v0, 1, v2
	v_add_u32_e32 v3, s12, v189
	v_and_b32_e32 v2, 31, v3
	v_lshrrev_b32_e32 v3, 5, v3
	v_and_b32_e32 v3, 1, v3
	v_lshlrev_b32_e32 v10, 4, v3
	v_mad_u32_u24 v9, v2, s73, v10
	v_and_b32_e32 v8, 1, v4
	ds_read_b128 v[212:215], v9
	ds_read_b128 v[216:219], v9 offset:32
	ds_read_b128 v[224:227], v9 offset:64
	s_waitcnt lgkmcnt(2)
	v_mfma_f32_32x32x16_bf16 v[96:111], v[212:215], v[136:139], 0
	ds_read_b128 v[212:215], v9 offset:96
	s_cmp_lt_i32 s46, 64
	s_cselect_b64 vcc, -1, 0
	s_cmp_gt_i32 s46, 63
	v_cndmask_b32_e32 v0, 0, v0, vcc
	s_cselect_b64 vcc, -1, 0
	v_lshlrev_b32_e32 v3, 2, v3
	s_waitcnt lgkmcnt(2)
	v_mfma_f32_32x32x16_bf16 v[96:111], v[216:219], v[112:115], v[96:111]
	ds_read_b128 v[216:219], v9 offset:128
	s_waitcnt lgkmcnt(2)
	v_mfma_f32_32x32x16_bf16 v[96:111], v[224:227], v[116:119], v[96:111]
	ds_read_b128 v[224:227], v9 offset:160
	s_waitcnt lgkmcnt(2)
	v_mfma_f32_32x32x16_bf16 v[96:111], v[212:215], v[120:123], v[96:111]
	ds_read_b128 v[212:215], v9 offset:192
	s_waitcnt lgkmcnt(2)
	v_mfma_f32_32x32x16_bf16 v[96:111], v[216:219], v[124:127], v[96:111]
	ds_read_b128 v[216:219], v9 offset:224
	s_waitcnt lgkmcnt(2)
	v_mfma_f32_32x32x16_bf16 v[96:111], v[224:227], v[128:131], v[96:111]
	ds_read_b128 v[224:227], v9 offset:8704
	s_waitcnt lgkmcnt(2)
	v_mfma_f32_32x32x16_bf16 v[96:111], v[212:215], v[132:135], v[96:111]
	ds_read_b128 v[212:215], v9 offset:8736
	s_waitcnt lgkmcnt(2)
	v_mfma_f32_32x32x16_bf16 v[96:111], v[216:219], v[140:143], v[96:111]
	ds_read_b128 v[216:219], v9 offset:8768
	s_waitcnt lgkmcnt(2)
	v_mfma_f32_32x32x16_bf16 v[80:95], v[224:227], v[136:139], 0
	ds_read_b128 v[224:227], v9 offset:8800
	s_waitcnt lgkmcnt(2)
	v_mfma_f32_32x32x16_bf16 v[80:95], v[212:215], v[112:115], v[80:95]
	ds_read_b128 v[212:215], v9 offset:8832
	s_waitcnt lgkmcnt(2)
	v_mfma_f32_32x32x16_bf16 v[80:95], v[216:219], v[116:119], v[80:95]
	ds_read_b128 v[216:219], v9 offset:8864
	s_waitcnt lgkmcnt(2)
	v_mfma_f32_32x32x16_bf16 v[80:95], v[224:227], v[120:123], v[80:95]
	ds_read_b128 v[224:227], v9 offset:8896
	s_waitcnt lgkmcnt(2)
	v_mfma_f32_32x32x16_bf16 v[80:95], v[212:215], v[124:127], v[80:95]
	ds_read_b128 v[212:215], v9 offset:8928
	s_waitcnt lgkmcnt(2)
	v_mfma_f32_32x32x16_bf16 v[80:95], v[216:219], v[128:131], v[80:95]
	s_waitcnt lgkmcnt(1)
	v_mfma_f32_32x32x16_bf16 v[80:95], v[224:227], v[132:135], v[80:95]
	s_waitcnt lgkmcnt(0)
	v_mfma_f32_32x32x16_bf16 v[80:95], v[212:215], v[140:143], v[80:95]
	v_cndmask_b32_e32 v4, 0, v8, vcc
	v_or_b32_e32 v0, v4, v0
	v_cmp_ne_u64_e32 vcc, 0, v[0:1]
	v_or_b32_e32 v0, s26, v3
	v_cmp_le_i32_e64 s[12:13], v0, v150
	s_and_b64 s[36:37], vcc, s[12:13]
	v_mov_b32_e32 v4, 0xf149f2ca
	v_mov_b32_e32 v5, 0xf149f2ca
	v_and_b32_e32 v226, 32, v189
	v_lshrrev_b32_e32 v226, 1, v226
	ds_read_b32 v213, v226 offset:43008
	ds_read_b32 v214, v226 offset:43012
	ds_read_b32 v215, v226 offset:43016
	ds_read_b32 v216, v226 offset:43020
	ds_read_b32 v217, v226 offset:43040
	ds_read_b32 v218, v226 offset:43044
	ds_read_b32 v224, v226 offset:43048
	ds_read_b32 v225, v226 offset:43052
	s_waitcnt lgkmcnt(0)
	v_sub_u32_e32 v213, v162, v213
	v_med3_i32 v213, v213, 0, v236
	v_lshl_add_u32 v213, v213, 2, v163
	ds_read_b32 v213, v213 offset:43264
	v_sub_u32_e32 v214, v162, v214
	v_med3_i32 v214, v214, 0, v236
	v_lshl_add_u32 v214, v214, 2, v163
	ds_read_b32 v214, v214 offset:43264
	v_sub_u32_e32 v215, v162, v215
	v_med3_i32 v215, v215, 0, v236
	v_lshl_add_u32 v215, v215, 2, v163
	ds_read_b32 v215, v215 offset:43264
	v_sub_u32_e32 v216, v162, v216
	v_med3_i32 v216, v216, 0, v236
	v_lshl_add_u32 v216, v216, 2, v163
	ds_read_b32 v216, v216 offset:43264
	v_sub_u32_e32 v217, v162, v217
	v_med3_i32 v217, v217, 0, v236
	v_lshl_add_u32 v217, v217, 2, v163
	ds_read_b32 v217, v217 offset:43264
	v_sub_u32_e32 v218, v162, v218
	v_med3_i32 v218, v218, 0, v236
	v_lshl_add_u32 v218, v218, 2, v163
	ds_read_b32 v218, v218 offset:43264
	v_sub_u32_e32 v224, v162, v224
	v_med3_i32 v224, v224, 0, v236
	v_lshl_add_u32 v224, v224, 2, v163
	ds_read_b32 v224, v224 offset:43264
	v_sub_u32_e32 v225, v162, v225
	v_med3_i32 v225, v225, 0, v236
	v_lshl_add_u32 v225, v225, 2, v163
	ds_read_b32 v225, v225 offset:43264
	s_waitcnt lgkmcnt(0)
	v_fmac_f32_e32 v213, 0x3e0293ee, v96
	v_cndmask_b32_e64 v5, v5, v213, s[36:37]

; #define MFMA32(a, b, c) __builtin_amdgcn_mfma_f32_32x32x16_bf16((a), (b), (c), 0, 0, 0)
;   DI float score(float s, int, float, int t) const { return mine(t) ? s * sc + bfar : NEG; }
; template <int DK, bool PV, class SF, class PH>
; DI void attn_tile(const bf16x8 (&qf)[DK / 16], f32x16 (&o)[4], float& m, float& l, const char* smem, SF sf, PH ph) {
;     ...
;   for (int kb = 0; kb < 2; ++kb) {
; #pragma unroll
;     for (int i = 0; i < 16; ++i) s[kb][i] = 0.f;
; #pragma unroll
;     for (int ks = 0; ks < DK / 16; ++ks) {
;       bf16x8 a = *(const bf16x8*)(Ks + (kb * 32 + r) * (DK + 8) + ks * 16 + h * 8);
;       s[kb] = MFMA32(a, qf[ks], s[kb]);
;     }
;   }
;   DI float score(float s, int key, float ax, int) const {
;     bool valid = key <= tq && (tq - key) < 512;
;     int d = posq - __float_as_int(ax);
;     d = d < 0 ? 0 : (d > 799 ? 799 : d);
;     return valid ? s * sc + lutr[d] : NEG;
;   }
.LBB0_779:
	s_or_b64 exec, exec, s[6:7]
	s_waitcnt vmcnt(7)
	ds_write_b128 v147, v[2:5]
	s_waitcnt vmcnt(6)
	ds_write_b128 v151, v[6:9]
	s_waitcnt vmcnt(5)
	ds_write_b128 v160, v[10:13]
	s_waitcnt vmcnt(4)
	ds_write_b128 v161, v[80:83]
	s_waitcnt vmcnt(3)
	ds_write2_b64 v165, v[84:85], v[86:87] offset1:1
	s_waitcnt vmcnt(2)
	ds_write2_b64 v166, v[88:89], v[90:91] offset1:1
	s_waitcnt vmcnt(1)
	ds_write2_b64 v167, v[92:93], v[94:95] offset1:1
	s_waitcnt vmcnt(0)
	ds_write2_b64 v168, v[96:97], v[98:99] offset1:1
	s_and_saveexec_b64 s[6:7], s[10:11]
	ds_write_b32 v145, v0 offset:43008
	s_or_b64 exec, exec, s[6:7]
	s_waitcnt lgkmcnt(0)
	s_barrier
	s_mov_b32 s6, 0
	s_nop 0
	v_add_u32_e32 v0, s6, v189
	v_and_b32_e32 v2, 31, v0
	v_lshrrev_b32_e32 v0, 5, v0
	v_and_b32_e32 v0, 1, v0
	v_lshlrev_b32_e32 v11, 4, v0
	v_mad_u32_u24 v3, v2, s73, v11
	ds_read_b128 v[212:215], v3
	ds_read_b128 v[216:219], v3 offset:32
	ds_read_b128 v[224:227], v3 offset:64
	s_waitcnt lgkmcnt(2)
	v_mfma_f32_32x32x16_bf16 v[96:111], v[212:215], v[136:139], 0
	ds_read_b128 v[212:215], v3 offset:96
	s_waitcnt lgkmcnt(2)
	v_mfma_f32_32x32x16_bf16 v[96:111], v[216:219], v[112:115], v[96:111]
	ds_read_b128 v[216:219], v3 offset:128
	s_waitcnt lgkmcnt(2)
	v_mfma_f32_32x32x16_bf16 v[96:111], v[224:227], v[116:119], v[96:111]
	ds_read_b128 v[224:227], v3 offset:160
	s_waitcnt lgkmcnt(2)
	v_mfma_f32_32x32x16_bf16 v[96:111], v[212:215], v[120:123], v[96:111]
	ds_read_b128 v[212:215], v3 offset:192
	s_waitcnt lgkmcnt(2)
	v_mfma_f32_32x32x16_bf16 v[96:111], v[216:219], v[124:127], v[96:111]
	ds_read_b128 v[216:219], v3 offset:224
	s_waitcnt lgkmcnt(2)
	v_mfma_f32_32x32x16_bf16 v[96:111], v[224:227], v[128:131], v[96:111]
	ds_read_b128 v[224:227], v3 offset:8704
	s_waitcnt lgkmcnt(2)
	v_mfma_f32_32x32x16_bf16 v[96:111], v[212:215], v[132:135], v[96:111]
	ds_read_b128 v[212:215], v3 offset:8736
	s_waitcnt lgkmcnt(2)
	v_mfma_f32_32x32x16_bf16 v[96:111], v[216:219], v[140:143], v[96:111]
	ds_read_b128 v[216:219], v3 offset:8768
	s_waitcnt lgkmcnt(2)
	v_mfma_f32_32x32x16_bf16 v[80:95], v[224:227], v[136:139], 0
	ds_read_b128 v[224:227], v3 offset:8800
	s_waitcnt lgkmcnt(2)
	v_mfma_f32_32x32x16_bf16 v[80:95], v[212:215], v[112:115], v[80:95]
	ds_read_b128 v[212:215], v3 offset:8832
	s_waitcnt lgkmcnt(2)
	v_mfma_f32_32x32x16_bf16 v[80:95], v[216:219], v[116:119], v[80:95]
	ds_read_b128 v[216:219], v3 offset:8864
	s_waitcnt lgkmcnt(2)
	v_mfma_f32_32x32x16_bf16 v[80:95], v[224:227], v[120:123], v[80:95]
	ds_read_b128 v[224:227], v3 offset:8896
	s_waitcnt lgkmcnt(2)
	v_mfma_f32_32x32x16_bf16 v[80:95], v[212:215], v[124:127], v[80:95]
	ds_read_b128 v[212:215], v3 offset:8928
	s_waitcnt lgkmcnt(2)
	v_mfma_f32_32x32x16_bf16 v[80:95], v[216:219], v[128:131], v[80:95]
	s_waitcnt lgkmcnt(1)
	v_mfma_f32_32x32x16_bf16 v[80:95], v[224:227], v[132:135], v[80:95]
	s_waitcnt lgkmcnt(0)
	v_mfma_f32_32x32x16_bf16 v[80:95], v[212:215], v[140:143], v[80:95]
	v_lshlrev_b32_e32 v4, 2, v0
	v_add_u32_e32 v0, s26, v4
	v_subrev_u32_e32 v3, 59, v0
	v_sub_u32_e32 v5, v146, v4
	v_cmp_le_i32_e32 vcc, v3, v150
	v_add_u32_e32 v3, 59, v5
	v_cmp_gt_i32_e64 s[12:13], s3, v3
	s_and_b64 s[12:13], vcc, s[12:13]
	v_mov_b32_e32 v3, 0xf149f2ca
	v_mov_b32_e32 v6, 0xf149f2ca
	v_and_b32_e32 v226, 32, v189
	v_lshrrev_b32_e32 v226, 1, v226
	ds_read_b32 v213, v226 offset:43008
	ds_read_b32 v214, v226 offset:43012
	ds_read_b32 v215, v226 offset:43016
	ds_read_b32 v216, v226 offset:43020
	ds_read_b32 v217, v226 offset:43040
	ds_read_b32 v218, v226 offset:43044
	ds_read_b32 v224, v226 offset:43048
	ds_read_b32 v225, v226 offset:43052
	s_waitcnt lgkmcnt(0)
	v_sub_u32_e32 v213, v162, v213
	v_med3_i32 v213, v213, 0, v236
	v_lshl_add_u32 v213, v213, 2, v163
	ds_read_b32 v213, v213 offset:43264
	v_sub_u32_e32 v214, v162, v214
	v_med3_i32 v214, v214, 0, v236
	v_lshl_add_u32 v214, v214, 2, v163
	ds_read_b32 v214, v214 offset:43264
	v_sub_u32_e32 v215, v162, v215
	v_med3_i32 v215, v215, 0, v236
	v_lshl_add_u32 v215, v215, 2, v163
	ds_read_b32 v215, v215 offset:43264
	v_sub_u32_e32 v216, v162, v216
	v_med3_i32 v216, v216, 0, v236
	v_lshl_add_u32 v216, v216, 2, v163
	ds_read_b32 v216, v216 offset:43264
	v_sub_u32_e32 v217, v162, v217
	v_med3_i32 v217, v217, 0, v236
	v_lshl_add_u32 v217, v217, 2, v163
	ds_read_b32 v217, v217 offset:43264
	v_sub_u32_e32 v218, v162, v218
	v_med3_i32 v218, v218, 0, v236
	v_lshl_add_u32 v218, v218, 2, v163
	ds_read_b32 v218, v218 offset:43264
	v_sub_u32_e32 v224, v162, v224
	v_med3_i32 v224, v224, 0, v236
	v_lshl_add_u32 v224, v224, 2, v163
	ds_read_b32 v224, v224 offset:43264
	v_sub_u32_e32 v225, v162, v225
	v_med3_i32 v225, v225, 0, v236
	v_lshl_add_u32 v225, v225, 2, v163
	ds_read_b32 v225, v225 offset:43264
	s_waitcnt lgkmcnt(0)
	v_fmac_f32_e32 v213, 0x3e0293ee, v96
	v_cndmask_b32_e64 v6, v6, v213, s[12:13]
